# mixers re-dealt: workgroups with a 4th W_in tile take 2 LRU items and no attention item, the others 4 attention items
# baseline (speedup 1.0000x reference)
.LBB0_312:
	s_or_b64 exec, exec, s[50:51]
	v_mov_b32_e32 v0, v176
	s_cmp_eq_u32 s68, 0x100
	s_cbranch_scc0 .Lrm_orig_lru_9673
	s_lshr_b32 s98, s2, 3
	s_cmp_lt_u32 s98, 16
	s_cbranch_scc1 .Llru_low_lru_9673
	s_movk_i32 s3, 0x100
	s_movk_i32 s99, 0x7ff
	s_mov_b32 s10, s68
	s_branch .Lrm_done_lru_9673
.Llru_low_lru_9673:
	s_and_b32 s3, s2, 7
	s_lshl_b32 s99, s3, 8
	s_or_b32 s99, s99, 0xff
	s_lshl_b32 s3, s3, 5
	s_add_i32 s3, s3, s98
	s_mov_b32 s10, 16
	s_branch .Lrm_done_lru_9673
.Lrm_orig_lru_9673:
	s_mov_b32 s3, s2
	s_mov_b32 s10, s68
	s_movk_i32 s99, 0x7ff
.Lrm_done_lru_9673:
	s_waitcnt lgkmcnt(0)
	s_barrier
	v_writelane_b32 v255, s3, 0
	v_writelane_b32 v255, s10, 1
	v_writelane_b32 v255, s11, 2
	v_writelane_b32 v255, s12, 3
	v_writelane_b32 v255, s13, 4
	v_writelane_b32 v255, s14, 5
	v_writelane_b32 v255, s15, 6
	v_writelane_b32 v255, s16, 7
	v_writelane_b32 v255, s17, 8
	v_writelane_b32 v255, s20, 9
	v_writelane_b32 v255, s21, 10
	v_writelane_b32 v255, s28, 11
	v_writelane_b32 v255, s30, 12
	v_writelane_b32 v255, s34, 13
	v_writelane_b32 v255, s38, 14
	v_writelane_b32 v255, s48, 15
	v_writelane_b32 v255, s49, 16
	v_writelane_b32 v255, s52, 17
	v_writelane_b32 v255, s53, 18
	v_writelane_b32 v255, s54, 19
	v_writelane_b32 v255, s56, 20
	v_writelane_b32 v255, s57, 21
	v_writelane_b32 v255, s69, 22
	s_add_i32 s2, s2, 0x300
	s_mov_b64 s[6:7], s[0:1]
	s_cmpk_lt_i32 s2, 0x380
	s_waitcnt vmcnt(0)
	v_mov_b64_e32 v[0:1], s[6:7]
	flat_load_dwordx2 v[4:5], v[0:1] offset:216
	s_cselect_b64 s[48:49], -1, 0
	s_ashr_i32 s69, s68, 31
	v_mov_b32_e32 v14, v176
	s_cmpk_gt_i32 s2, 0x37f
	s_nop 0
	v_readfirstlane_b32 s6, v14
	s_cbranch_scc1 .Lwb0_after
	s_lshr_b32 s3, s33, 29
	s_add_i32 s3, s2, s3
	s_ashr_i32 s7, s3, 3
	s_and_b32 s3, s3, -8
	s_sub_i32 s3, s2, s3
	s_cmp_lt_i32 s3, 0
	s_movk_i32 s10, 0x71
	s_cselect_b32 s10, s10, 0x70
	s_mul_i32 s3, s10, s3
	s_add_i32 s3, s3, s7
	s_mul_hi_i32 s7, s3, 0x92492493
	s_add_i32 s7, s7, s3
	s_lshr_b32 s10, s7, 31
	s_ashr_i32 s7, s7, 5
	s_add_i32 s7, s7, s10
	s_lshl_b32 s10, s7, 3
	s_mul_i32 s7, s7, 56
	s_sub_i32 s3, s3, s7
	s_bfe_i32 s7, s3, 0x80000
	s_bfe_u32 s7, s7, 0x3000c
	s_add_i32 s11, s3, s7
	s_bfe_i32 s7, s11, 0x80000
	s_and_b32 s11, s11, 0xf8
	s_sub_i32 s3, s3, s11
	s_sext_i32_i8 s3, s3
	s_sext_i32_i16 s7, s7
	s_add_i32 s30, s10, s3
	s_mov_b64 s[8:9], 0x1a100000
	s_lshr_b32 s7, s7, 3
	s_ashr_i32 s31, s30, 31
	v_readfirstlane_b32 s3, v176
	s_cmpk_gt_u32 s3, 0xff
	s_waitcnt vmcnt(0) lgkmcnt(0)
	v_lshl_add_u64 v[128:129], v[4:5], 0, s[8:9]
	s_cbranch_scc1 .Lwb0_BB0_250
	s_lshl_b64 s[8:9], s[30:31], 8
	s_and_b32 s10, s3, 0xc0
	s_lshl_b32 s3, s3, 4
	s_or_b32 s8, s8, s10
	s_and_b32 s3, s3, 0xc00
	v_mov_b32_e32 v1, s9
	v_or_b32_e32 v0, s8, v177
	s_add_i32 s3, s3, 0
	v_lshl_add_u64 v[0:1], v[0:1], 4, v[128:129]
	s_add_i32 m0, s3, 0x21c00
	s_nop 0
	global_load_lds_dwordx4 v[0:1], off

.LBB0_318:
	v_add_u32_e32 v70, s6, v122
	ds_read_b64 v[66:67], v70
	s_addk_i32 s6, 0x800
	s_cmpk_eq_i32 s6, 0x2000
	s_waitcnt lgkmcnt(0)
	v_mul_f32_e32 v71, v96, v66
	v_fmac_f32_e32 v67, v101, v66
	v_cvt_pk_bf16_f32 v66, v71, v67
	ds_read_b64 v[68:69], v70 offset:512
	global_store_dword v[64:65], v66, off offset:-2048 nt
	s_waitcnt lgkmcnt(0)
	v_mul_f32_e32 v71, v71, v68
	v_fmac_f32_e32 v69, v67, v68
	v_cvt_pk_bf16_f32 v68, v71, v69
	ds_read_b64 v[66:67], v70 offset:1024
	global_store_dword v[64:65], v68, off offset:-1024 nt
	s_waitcnt lgkmcnt(0)
	v_mul_f32_e32 v68, v71, v66
	v_fmac_f32_e32 v67, v69, v66
	v_cvt_pk_bf16_f32 v66, v68, v67
	ds_read_b64 v[100:101], v70 offset:1536
	global_store_dword v[64:65], v66, off nt
	s_waitcnt lgkmcnt(0)
	v_mul_f32_e32 v96, v68, v100
	v_fmac_f32_e32 v101, v67, v100
	v_cvt_pk_bf16_f32 v66, v96, v101
	global_store_dword v[64:65], v66, off offset:1024 nt
	v_lshl_add_u64 v[64:65], v[64:65], 0, s[14:15]
	s_cbranch_scc0 .LBB0_318
	s_add_i32 s95, s95, 1
	s_cmp_eq_u32 s95, 4
	v_lshl_add_u64 v[98:99], v[98:99], 0, s[16:17]
	s_cbranch_scc0 .LBB0_317
	s_lshl_b32 s6, s18, 6
	s_or_b32 s6, s6, s94
	s_ashr_i32 s7, s6, 31
	s_lshl_b64 s[6:7], s[6:7], 11
	v_lshl_add_u64 v[0:1], v[94:95], 0, s[6:7]
	v_lshl_add_u64 v[0:1], v[0:1], 0, v[80:81]
	v_add_co_u32_e32 v0, vcc, 0x1a000000, v0
	s_add_i32 s3, s3, s20
	s_nop 0
	v_addc_co_u32_e32 v1, vcc, 0, v1, vcc
	v_mov_b32_e32 v97, v101
	s_cmp_gt_i32 s3, s99
	global_store_dwordx2 v[0:1], v[96:97], off
	s_cbranch_scc0 .LBB0_314
.LBB0_321:
	v_mov_b32_e32 v0, v176
	s_cmp_eq_u32 s68, 0x100
	s_cbranch_scc0 .Lrm_orig_attn_12323
	s_and_b32 s3, s2, 7
	s_lshl_b32 s3, s3, 6
	s_lshr_b32 s98, s2, 3
	s_cmp_lt_u32 s98, 16
	s_cbranch_scc1 .Lat_low_attn_12323
	s_sub_i32 s98, s98, 16
	s_lshl_b32 s98, s98, 2
	s_add_i32 s3, s3, s98
	s_add_i32 s99, s3, 3
	s_branch .Lat_done_attn_12323
.Lat_low_attn_12323:
	s_movk_i32 s3, 0x200
	s_movk_i32 s99, 0x1ff

.LBB0_1049:
	s_or_b64 exec, exec, s[48:49]
	v_mov_b32_e32 v0, v176
	s_cmp_eq_u32 s68, 0x100
	s_cbranch_scc0 .Lrm_orig_lru_31452
	s_lshr_b32 s98, s2, 3
	s_cmp_lt_u32 s98, 16
	s_cbranch_scc1 .Llru_low_lru_31452
	s_movk_i32 s3, 0x100
	s_movk_i32 s99, 0x7ff
	s_mov_b32 s12, s68
	s_branch .Lrm_done_lru_31452
.Llru_low_lru_31452:
	s_and_b32 s3, s2, 7
	s_lshl_b32 s99, s3, 8
	s_or_b32 s99, s99, 0xff
	s_lshl_b32 s3, s3, 5
	s_add_i32 s3, s3, s98
	s_mov_b32 s12, 16
	s_branch .Lrm_done_lru_31452
.Lrm_orig_lru_31452:
	s_mov_b32 s3, s2
	s_mov_b32 s12, s68
	s_movk_i32 s99, 0x7ff

.LBB0_1055:
	v_add_u32_e32 v70, s8, v122
	ds_read_b64 v[66:67], v70
	s_addk_i32 s8, 0x800
	s_cmpk_eq_i32 s8, 0x2000
	s_waitcnt lgkmcnt(0)
	v_mul_f32_e32 v71, v96, v66
	v_fmac_f32_e32 v67, v101, v66
	v_cvt_pk_bf16_f32 v66, v71, v67
	ds_read_b64 v[68:69], v70 offset:512
	global_store_dword v[64:65], v66, off offset:-2048 nt
	s_waitcnt lgkmcnt(0)
	v_mul_f32_e32 v71, v71, v68
	v_fmac_f32_e32 v69, v67, v68
	v_cvt_pk_bf16_f32 v68, v71, v69
	ds_read_b64 v[66:67], v70 offset:1024
	global_store_dword v[64:65], v68, off offset:-1024 nt
	s_waitcnt lgkmcnt(0)
	v_mul_f32_e32 v68, v71, v66
	v_fmac_f32_e32 v67, v69, v66
	v_cvt_pk_bf16_f32 v66, v68, v67
	ds_read_b64 v[100:101], v70 offset:1536
	global_store_dword v[64:65], v66, off nt
	s_waitcnt lgkmcnt(0)
	v_mul_f32_e32 v96, v68, v100
	v_fmac_f32_e32 v101, v67, v100
	v_cvt_pk_bf16_f32 v66, v96, v101
	global_store_dword v[64:65], v66, off offset:1024 nt
	v_lshl_add_u64 v[64:65], v[64:65], 0, s[14:15]
	s_cbranch_scc0 .LBB0_1055
	s_add_i32 s95, s95, 1
	s_cmp_eq_u32 s95, 4
	v_lshl_add_u64 v[98:99], v[98:99], 0, s[20:21]
	s_cbranch_scc0 .LBB0_1054
	s_lshl_b32 s8, s22, 6
	s_or_b32 s8, s8, s94
	s_ashr_i32 s9, s8, 31
	s_lshl_b64 s[8:9], s[8:9], 11
	v_lshl_add_u64 v[0:1], v[94:95], 0, s[8:9]
	v_lshl_add_u64 v[0:1], v[0:1], 0, v[80:81]
	v_add_co_u32_e32 v0, vcc, 0x1a000000, v0
	s_add_i32 s3, s3, s26
	s_nop 0
	v_addc_co_u32_e32 v1, vcc, 0, v1, vcc
	v_mov_b32_e32 v97, v101
	s_cmp_gt_i32 s3, s99
	global_store_dwordx2 v[0:1], v[96:97], off
	s_cbranch_scc0 .LBB0_1051
